# v38 + one LDS wait per two PV MFMAs in the diff softmax/PV blocks
# speedup vs baseline: 1.0058x; 1.0058x over previous
.LBB0_637:
	s_mulk_i32 s24, 0x5000
	v_add_u32_e32 v32, s24, v194
	s_setprio 1
	ds_read_b64_tr_b16 v[214:215], v32 offset:18432
	ds_read_b64_tr_b16 v[216:217], v32 offset:20992
	ds_read_b64_tr_b16 v[218:219], v32 offset:18496
	ds_read_b64_tr_b16 v[220:221], v32 offset:21056
	ds_read_b64_tr_b16 v[222:223], v32 offset:18560
	ds_read_b64_tr_b16 v[224:225], v32 offset:21120
	ds_read_b64_tr_b16 v[226:227], v32 offset:18624
	ds_read_b64_tr_b16 v[228:229], v32 offset:21184
	ds_read_b64_tr_b16 v[230:231], v32 offset:23552
	ds_read_b64_tr_b16 v[232:233], v32 offset:26112
	v_exp_f32_e32 v114, v114
	v_exp_f32_e32 v115, v115
	v_exp_f32_e32 v116, v116
	v_exp_f32_e32 v117, v117
	v_exp_f32_e32 v118, v118
	v_cvt_pk_bf16_f32 v234, v114, v115
	v_exp_f32_e32 v119, v119
	v_cvt_pk_bf16_f32 v235, v116, v117
	v_exp_f32_e32 v120, v120
	v_exp_f32_e32 v121, v121
	v_cvt_pk_bf16_f32 v236, v118, v119
	s_nop 0
	v_cvt_pk_bf16_f32 v237, v120, v121
	s_nop 1
	s_waitcnt lgkmcnt(6)
	v_mfma_f32_32x32x16_bf16 v[82:97], v[234:237], v[214:217], v[82:97]
	ds_read_b64_tr_b16 v[214:215], v32 offset:23616
	ds_read_b64_tr_b16 v[216:217], v32 offset:26176
	v_exp_f32_e32 v122, v122
	v_exp_f32_e32 v123, v123
	v_exp_f32_e32 v124, v124
	v_mfma_f32_32x32x16_bf16 v[66:81], v[234:237], v[218:221], v[66:81]
	ds_read_b64_tr_b16 v[218:219], v32 offset:23680
	ds_read_b64_tr_b16 v[220:221], v32 offset:26240
	v_exp_f32_e32 v125, v125
	v_exp_f32_e32 v126, v126
	v_exp_f32_e32 v127, v127
	v_cvt_pk_bf16_f32 v238, v122, v123
	v_add_f32_e32 v252, v114, v115
	s_waitcnt lgkmcnt(6)
	v_mfma_f32_32x32x16_bf16 v[50:65], v[234:237], v[222:225], v[50:65]
	ds_read_b64_tr_b16 v[222:223], v32 offset:23744
	ds_read_b64_tr_b16 v[224:225], v32 offset:26304
	v_exp_f32_e32 v128, v128
	v_exp_f32_e32 v129, v129
	v_cvt_pk_bf16_f32 v239, v124, v125
	v_add_f32_e32 v253, v116, v117
	v_mfma_f32_32x32x16_bf16 v[34:49], v[234:237], v[226:229], v[34:49]
	ds_read_b64_tr_b16 v[226:227], v32 offset:28672
	ds_read_b64_tr_b16 v[228:229], v32 offset:31232
	v_cvt_pk_bf16_f32 v240, v126, v127
	v_cvt_pk_bf16_f32 v241, v128, v129
	v_add_f32_e32 v254, v118, v119
	v_add_f32_e32 v213, v120, v121
	s_waitcnt lgkmcnt(6)
	v_mfma_f32_32x32x16_bf16 v[82:97], v[238:241], v[230:233], v[82:97]
	ds_read_b64_tr_b16 v[230:231], v32 offset:28736
	ds_read_b64_tr_b16 v[232:233], v32 offset:31296
	v_exp_f32_e32 v130, v130
	v_exp_f32_e32 v131, v131
	v_exp_f32_e32 v132, v132
	v_add_f32_e32 v252, v252, v122
	v_mfma_f32_32x32x16_bf16 v[66:81], v[238:241], v[214:217], v[66:81]
	ds_read_b64_tr_b16 v[214:215], v32 offset:28800
	ds_read_b64_tr_b16 v[216:217], v32 offset:31360
	v_exp_f32_e32 v133, v133
	v_exp_f32_e32 v134, v134
	v_exp_f32_e32 v135, v135
	v_cvt_pk_bf16_f32 v244, v130, v131
	v_add_f32_e32 v253, v253, v123
	s_waitcnt lgkmcnt(6)
	v_mfma_f32_32x32x16_bf16 v[50:65], v[238:241], v[218:221], v[50:65]
	ds_read_b64_tr_b16 v[218:219], v32 offset:28864
	ds_read_b64_tr_b16 v[220:221], v32 offset:31424
	v_exp_f32_e32 v136, v136
	v_exp_f32_e32 v137, v137
	v_cvt_pk_bf16_f32 v245, v132, v133
	v_add_f32_e32 v254, v254, v124
	v_add_f32_e32 v213, v213, v125
	v_mfma_f32_32x32x16_bf16 v[34:49], v[238:241], v[222:225], v[34:49]
	ds_read_b64_tr_b16 v[222:223], v32 offset:33792
	ds_read_b64_tr_b16 v[224:225], v32 offset:36352
	v_cvt_pk_bf16_f32 v246, v134, v135
	v_add_f32_e32 v252, v252, v126
	v_cvt_pk_bf16_f32 v247, v136, v137
	v_add_f32_e32 v253, v253, v127
	v_add_f32_e32 v254, v254, v128
	v_add_f32_e32 v213, v213, v129
	s_waitcnt lgkmcnt(6)
	v_mfma_f32_32x32x16_bf16 v[82:97], v[244:247], v[226:229], v[82:97]
	ds_read_b64_tr_b16 v[226:227], v32 offset:33856
	ds_read_b64_tr_b16 v[228:229], v32 offset:36416
	v_exp_f32_e32 v138, v138
	v_exp_f32_e32 v139, v139
	v_exp_f32_e32 v140, v140
	v_add_f32_e32 v252, v252, v130
	v_mfma_f32_32x32x16_bf16 v[66:81], v[244:247], v[230:233], v[66:81]
	ds_read_b64_tr_b16 v[230:231], v32 offset:33920
	ds_read_b64_tr_b16 v[232:233], v32 offset:36480
	v_exp_f32_e32 v141, v141
	v_exp_f32_e32 v142, v142
	v_exp_f32_e32 v143, v143
	v_cvt_pk_bf16_f32 v248, v138, v139
	v_add_f32_e32 v253, v253, v131
	s_waitcnt lgkmcnt(6)
	v_mfma_f32_32x32x16_bf16 v[50:65], v[244:247], v[214:217], v[50:65]
	ds_read_b64_tr_b16 v[214:215], v32 offset:33984
	ds_read_b64_tr_b16 v[216:217], v32 offset:36544
	v_exp_f32_e32 v144, v144
	v_exp_f32_e32 v145, v145
	v_cvt_pk_bf16_f32 v249, v140, v141
	v_add_f32_e32 v254, v254, v132
	v_add_f32_e32 v213, v213, v133
	v_mfma_f32_32x32x16_bf16 v[34:49], v[244:247], v[218:221], v[34:49]
	v_cvt_pk_bf16_f32 v250, v142, v143
	v_add_f32_e32 v252, v252, v134
	v_cvt_pk_bf16_f32 v251, v144, v145
	v_add_f32_e32 v253, v253, v135
	v_add_f32_e32 v254, v254, v136
	v_add_f32_e32 v213, v213, v137
	s_waitcnt lgkmcnt(4)
	v_mfma_f32_32x32x16_bf16 v[82:97], v[248:251], v[222:225], v[82:97]
	v_add_f32_e32 v252, v252, v138
	v_add_f32_e32 v253, v253, v139
	v_add_f32_e32 v254, v254, v140
	v_mfma_f32_32x32x16_bf16 v[66:81], v[248:251], v[226:229], v[66:81]
	v_add_f32_e32 v213, v213, v141
	v_add_f32_e32 v252, v252, v142
	v_add_f32_e32 v253, v253, v143
	s_waitcnt lgkmcnt(0)
	v_mfma_f32_32x32x16_bf16 v[50:65], v[248:251], v[230:233], v[50:65]
	v_add_f32_e32 v254, v254, v144
	v_add_f32_e32 v213, v213, v145
	v_add_f32_e32 v252, v252, v253
	v_add_f32_e32 v254, v254, v213
	v_mfma_f32_32x32x16_bf16 v[34:49], v[248:251], v[214:217], v[34:49]
	v_add_f32_e32 v252, v252, v254
	v_add_f32_e32 v182, v182, v252
	s_setprio 0

.LBB0_837:
	s_mulk_i32 s35, 0x5000
	v_add_u32_e32 v32, s35, v194
	s_setprio 1
	ds_read_b64_tr_b16 v[214:215], v32 offset:18432
	ds_read_b64_tr_b16 v[216:217], v32 offset:20992
	ds_read_b64_tr_b16 v[218:219], v32 offset:18496
	ds_read_b64_tr_b16 v[220:221], v32 offset:21056
	ds_read_b64_tr_b16 v[222:223], v32 offset:18560
	ds_read_b64_tr_b16 v[224:225], v32 offset:21120
	ds_read_b64_tr_b16 v[226:227], v32 offset:18624
	ds_read_b64_tr_b16 v[228:229], v32 offset:21184
	ds_read_b64_tr_b16 v[230:231], v32 offset:23552
	ds_read_b64_tr_b16 v[232:233], v32 offset:26112
	v_exp_f32_e32 v114, v114
	v_exp_f32_e32 v115, v115
	v_exp_f32_e32 v116, v116
	v_exp_f32_e32 v117, v117
	v_exp_f32_e32 v118, v118
	v_cvt_pk_bf16_f32 v234, v114, v115
	v_exp_f32_e32 v119, v119
	v_cvt_pk_bf16_f32 v235, v116, v117
	v_exp_f32_e32 v120, v120
	v_exp_f32_e32 v121, v121
	v_cvt_pk_bf16_f32 v236, v118, v119
	s_nop 0
	v_cvt_pk_bf16_f32 v237, v120, v121
	s_nop 1
	s_waitcnt lgkmcnt(6)
	v_mfma_f32_32x32x16_bf16 v[82:97], v[234:237], v[214:217], v[82:97]
	ds_read_b64_tr_b16 v[214:215], v32 offset:23616
	ds_read_b64_tr_b16 v[216:217], v32 offset:26176
	v_exp_f32_e32 v122, v122
	v_exp_f32_e32 v123, v123
	v_exp_f32_e32 v124, v124
	v_mfma_f32_32x32x16_bf16 v[66:81], v[234:237], v[218:221], v[66:81]
	ds_read_b64_tr_b16 v[218:219], v32 offset:23680
	ds_read_b64_tr_b16 v[220:221], v32 offset:26240
	v_exp_f32_e32 v125, v125
	v_exp_f32_e32 v126, v126
	v_exp_f32_e32 v127, v127
	v_cvt_pk_bf16_f32 v238, v122, v123
	v_add_f32_e32 v252, v114, v115
	s_waitcnt lgkmcnt(6)
	v_mfma_f32_32x32x16_bf16 v[50:65], v[234:237], v[222:225], v[50:65]
	ds_read_b64_tr_b16 v[222:223], v32 offset:23744
	ds_read_b64_tr_b16 v[224:225], v32 offset:26304
	v_exp_f32_e32 v128, v128
	v_exp_f32_e32 v129, v129
	v_cvt_pk_bf16_f32 v239, v124, v125
	v_add_f32_e32 v253, v116, v117
	v_mfma_f32_32x32x16_bf16 v[34:49], v[234:237], v[226:229], v[34:49]
	ds_read_b64_tr_b16 v[226:227], v32 offset:28672
	ds_read_b64_tr_b16 v[228:229], v32 offset:31232
	v_cvt_pk_bf16_f32 v240, v126, v127
	v_cvt_pk_bf16_f32 v241, v128, v129
	v_add_f32_e32 v254, v118, v119
	v_add_f32_e32 v213, v120, v121
	s_waitcnt lgkmcnt(6)
	v_mfma_f32_32x32x16_bf16 v[82:97], v[238:241], v[230:233], v[82:97]
	ds_read_b64_tr_b16 v[230:231], v32 offset:28736
	ds_read_b64_tr_b16 v[232:233], v32 offset:31296
	v_exp_f32_e32 v130, v130
	v_exp_f32_e32 v131, v131
	v_exp_f32_e32 v132, v132
	v_add_f32_e32 v252, v252, v122
	v_mfma_f32_32x32x16_bf16 v[66:81], v[238:241], v[214:217], v[66:81]
	ds_read_b64_tr_b16 v[214:215], v32 offset:28800
	ds_read_b64_tr_b16 v[216:217], v32 offset:31360
	v_exp_f32_e32 v133, v133
	v_exp_f32_e32 v134, v134
	v_exp_f32_e32 v135, v135
	v_cvt_pk_bf16_f32 v244, v130, v131
	v_add_f32_e32 v253, v253, v123
	s_waitcnt lgkmcnt(6)
	v_mfma_f32_32x32x16_bf16 v[50:65], v[238:241], v[218:221], v[50:65]
	ds_read_b64_tr_b16 v[218:219], v32 offset:28864
	ds_read_b64_tr_b16 v[220:221], v32 offset:31424
	v_exp_f32_e32 v136, v136
	v_exp_f32_e32 v137, v137
	v_cvt_pk_bf16_f32 v245, v132, v133
	v_add_f32_e32 v254, v254, v124
	v_add_f32_e32 v213, v213, v125
	v_mfma_f32_32x32x16_bf16 v[34:49], v[238:241], v[222:225], v[34:49]
	ds_read_b64_tr_b16 v[222:223], v32 offset:33792
	ds_read_b64_tr_b16 v[224:225], v32 offset:36352
	v_cvt_pk_bf16_f32 v246, v134, v135
	v_add_f32_e32 v252, v252, v126
	v_cvt_pk_bf16_f32 v247, v136, v137
	v_add_f32_e32 v253, v253, v127
	v_add_f32_e32 v254, v254, v128
	v_add_f32_e32 v213, v213, v129
	s_waitcnt lgkmcnt(6)
	v_mfma_f32_32x32x16_bf16 v[82:97], v[244:247], v[226:229], v[82:97]
	ds_read_b64_tr_b16 v[226:227], v32 offset:33856
	ds_read_b64_tr_b16 v[228:229], v32 offset:36416
	v_exp_f32_e32 v138, v138
	v_exp_f32_e32 v139, v139
	v_exp_f32_e32 v140, v140
	v_add_f32_e32 v252, v252, v130
	v_mfma_f32_32x32x16_bf16 v[66:81], v[244:247], v[230:233], v[66:81]
	ds_read_b64_tr_b16 v[230:231], v32 offset:33920
	ds_read_b64_tr_b16 v[232:233], v32 offset:36480
	v_exp_f32_e32 v141, v141
	v_exp_f32_e32 v142, v142
	v_exp_f32_e32 v143, v143
	v_cvt_pk_bf16_f32 v248, v138, v139
	v_add_f32_e32 v253, v253, v131
	s_waitcnt lgkmcnt(6)
	v_mfma_f32_32x32x16_bf16 v[50:65], v[244:247], v[214:217], v[50:65]
	ds_read_b64_tr_b16 v[214:215], v32 offset:33984
	ds_read_b64_tr_b16 v[216:217], v32 offset:36544
	v_exp_f32_e32 v144, v144
	v_exp_f32_e32 v145, v145
	v_cvt_pk_bf16_f32 v249, v140, v141
	v_add_f32_e32 v254, v254, v132
	v_add_f32_e32 v213, v213, v133
	v_mfma_f32_32x32x16_bf16 v[34:49], v[244:247], v[218:221], v[34:49]
	v_cvt_pk_bf16_f32 v250, v142, v143
	v_add_f32_e32 v252, v252, v134
	v_cvt_pk_bf16_f32 v251, v144, v145
	v_add_f32_e32 v253, v253, v135
	v_add_f32_e32 v254, v254, v136
	v_add_f32_e32 v213, v213, v137
	s_waitcnt lgkmcnt(4)
	v_mfma_f32_32x32x16_bf16 v[82:97], v[248:251], v[222:225], v[82:97]
	v_add_f32_e32 v252, v252, v138
	v_add_f32_e32 v253, v253, v139
	v_add_f32_e32 v254, v254, v140
	v_mfma_f32_32x32x16_bf16 v[66:81], v[248:251], v[226:229], v[66:81]
	v_add_f32_e32 v213, v213, v141
	v_add_f32_e32 v252, v252, v142
	v_add_f32_e32 v253, v253, v143
	s_waitcnt lgkmcnt(0)
	v_mfma_f32_32x32x16_bf16 v[50:65], v[248:251], v[230:233], v[50:65]
	v_add_f32_e32 v254, v254, v144
	v_add_f32_e32 v213, v213, v145
	v_add_f32_e32 v252, v252, v253
	v_add_f32_e32 v254, v254, v213
	v_mfma_f32_32x32x16_bf16 v[34:49], v[248:251], v[214:217], v[34:49]
	v_add_f32_e32 v252, v252, v254
	v_add_f32_e32 v182, v182, v252
	s_setprio 0
